# out-proj residual epilogue de-serialised (all loads up front, counted waits); GEMM tile headers wait only for the prefetched slice (counted vmcnt), not the previous tile's stores
# speedup vs baseline: 1.0404x; 1.0139x over previous
.LBB0_888:
	v_add_u32_e32 v95, v125, v128
	ds_read_b128 v[96:99], v95 offset:16384
	ds_read_b128 v[100:103], v95 offset:18432
	ds_read_b128 v[104:107], v95 offset:20480
	ds_read_b128 v[108:111], v95 offset:22528
	v_add_u32_e32 v95, v126, v128
	ds_read_b128 v[130:133], v95 offset:49152
	ds_read_b128 v[134:137], v95 offset:51200
	ds_read_b128 v[138:141], v95 offset:53248
	ds_read_b128 v[142:145], v95 offset:55296
	v_add_u32_e32 v95, v125, v129
	ds_read_b128 v[214:217], v95 offset:16384
	ds_read_b128 v[218:221], v95 offset:18432
	ds_read_b128 v[222:225], v95 offset:20480
	ds_read_b128 v[226:229], v95 offset:22528
	v_add_u32_e32 v95, v126, v129
	ds_read_b128 v[230:233], v95 offset:49152
	ds_read_b128 v[234:237], v95 offset:51200
	ds_read_b128 v[238:241], v95 offset:53248
	s_setprio 1
	s_waitcnt lgkmcnt(7)
	ds_read_b128 v[242:245], v95 offset:55296
	v_mfma_f32_16x16x32_bf16 v[2:5], v[130:133], v[96:99], v[2:5]
	v_mfma_f32_16x16x32_bf16 v[6:9], v[134:137], v[96:99], v[6:9]
	v_mfma_f32_16x16x32_bf16 v[10:13], v[138:141], v[96:99], v[10:13]
	v_mfma_f32_16x16x32_bf16 v[14:17], v[142:145], v[96:99], v[14:17]
	v_mfma_f32_16x16x32_bf16 v[18:21], v[130:133], v[100:103], v[18:21]
	v_mfma_f32_16x16x32_bf16 v[22:25], v[134:137], v[100:103], v[22:25]
	v_mfma_f32_16x16x32_bf16 v[26:29], v[138:141], v[100:103], v[26:29]
	v_mfma_f32_16x16x32_bf16 v[30:33], v[142:145], v[100:103], v[30:33]
	v_mfma_f32_16x16x32_bf16 v[34:37], v[130:133], v[104:107], v[34:37]
	v_mfma_f32_16x16x32_bf16 v[38:41], v[134:137], v[104:107], v[38:41]
	v_mfma_f32_16x16x32_bf16 v[96:99], v[138:141], v[104:107], v[42:45]
	v_mfma_f32_16x16x32_bf16 v[100:103], v[142:145], v[104:107], v[46:49]
	v_mfma_f32_16x16x32_bf16 v[50:53], v[130:133], v[108:111], v[50:53]
	v_mfma_f32_16x16x32_bf16 v[54:57], v[134:137], v[108:111], v[54:57]
	v_mfma_f32_16x16x32_bf16 v[58:61], v[138:141], v[108:111], v[58:61]
	v_mfma_f32_16x16x32_bf16 v[62:65], v[142:145], v[108:111], v[62:65]
	s_waitcnt lgkmcnt(0)
	v_mfma_f32_16x16x32_bf16 v[146:149], v[230:233], v[214:217], v[2:5]
	v_mfma_f32_16x16x32_bf16 v[6:9], v[234:237], v[214:217], v[6:9]
	v_mfma_f32_16x16x32_bf16 v[150:153], v[238:241], v[214:217], v[10:13]
	v_mfma_f32_16x16x32_bf16 v[154:157], v[242:245], v[214:217], v[14:17]
	v_mfma_f32_16x16x32_bf16 v[158:161], v[230:233], v[218:221], v[18:21]
	v_mfma_f32_16x16x32_bf16 v[162:165], v[234:237], v[218:221], v[22:25]
	v_mfma_f32_16x16x32_bf16 v[166:169], v[238:241], v[218:221], v[26:29]
	v_mfma_f32_16x16x32_bf16 v[176:179], v[242:245], v[218:221], v[30:33]
	v_mfma_f32_16x16x32_bf16 v[46:49], v[230:233], v[222:225], v[34:37]
	v_mfma_f32_16x16x32_bf16 v[42:45], v[234:237], v[222:225], v[38:41]
	v_mfma_f32_16x16x32_bf16 v[38:41], v[238:241], v[222:225], v[96:99]
	v_mfma_f32_16x16x32_bf16 v[22:25], v[242:245], v[222:225], v[100:103]
	v_mfma_f32_16x16x32_bf16 v[18:21], v[230:233], v[226:229], v[50:53]
	v_mfma_f32_16x16x32_bf16 v[14:17], v[234:237], v[226:229], v[54:57]
	v_mfma_f32_16x16x32_bf16 v[10:13], v[238:241], v[226:229], v[58:61]
	v_mfma_f32_16x16x32_bf16 v[2:5], v[242:245], v[226:229], v[62:65]
	s_setprio 0
	s_min_i32 s0, s40, 0x4000
	s_ashr_i32 s0, s0, 11
	s_add_i32 s0, s0, s25
	s_mul_hi_i32 s1, s0, 0x6000
	s_mulk_i32 s0, 0x6000
	s_add_u32 s19, s94, s0
	s_addc_u32 s27, s95, s1
	s_lshl_b64 s[0:1], s[42:43], 2
	v_add_u32_e32 v28, s40, v127
	s_add_u32 s26, s19, s0
	v_ashrrev_i32_e32 v29, 31, v28
	s_addc_u32 s27, s27, s1
	v_lshlrev_b64 v[28:29], 12, v[28:29]
	v_lshl_add_u64 v[26:27], s[26:27], 0, v[0:1]
	v_mov_b32_e32 v95, v1
	v_lshl_add_u64 v[28:29], s[94:95], 0, v[28:29]
	v_lshl_add_u64 v[26:27], v[26:27], 0, v[94:95]
	s_mov_b64 s[26:27], 0x13582000
	v_lshl_add_u64 v[28:29], v[28:29], 0, s[0:1]
	s_mov_b32 s0, 0x13582000
	v_lshl_add_u64 v[52:53], v[26:27], 0, s[26:27]
	v_add_co_u32_e32 v26, vcc, s0, v26
	v_lshl_add_u64 v[28:29], v[28:29], 0, v[0:1]
	s_nop 0
	v_addc_co_u32_e32 v27, vcc, 0, v27, vcc
	v_lshl_add_u64 v[50:51], v[28:29], 0, v[94:95]
	global_load_dwordx4 v[26:29], v[52:53], off
	global_load_dwordx4 v[30:33], v[52:53], off offset:64
	global_load_dwordx4 v[34:37], v[52:53], off offset:128
	global_load_dwordx4 v[180:183], v[52:53], off offset:192
	v_add_co_u32_e32 v56, vcc, s96, v50
	s_mov_b32 s0, 0x30000
	s_nop 0
	v_addc_co_u32_e32 v57, vcc, 0, v51, vcc
	v_add_co_u32_e32 v184, vcc, s24, v50
	s_nop 1
	v_addc_co_u32_e32 v185, vcc, 0, v51, vcc
	v_add_co_u32_e32 v186, vcc, s0, v50
	s_nop 1
	v_addc_co_u32_e32 v187, vcc, 0, v51, vcc
	global_load_dwordx4 v[214:217], v[50:51], off
	global_load_dwordx4 v[218:221], v[50:51], off offset:64
	global_load_dwordx4 v[222:225], v[50:51], off offset:128
	global_load_dwordx4 v[226:229], v[50:51], off offset:192
	global_load_dwordx4 v[230:233], v[56:57], off
	global_load_dwordx4 v[234:237], v[56:57], off offset:64
	global_load_dwordx4 v[238:241], v[56:57], off offset:128
	global_load_dwordx4 v[242:245], v[56:57], off offset:192
	global_load_dwordx4 v[96:99], v[184:185], off
	global_load_dwordx4 v[100:103], v[184:185], off offset:64
	global_load_dwordx4 v[104:107], v[184:185], off offset:128
	global_load_dwordx4 v[108:111], v[184:185], off offset:192
	global_load_dwordx4 v[130:133], v[186:187], off
	global_load_dwordx4 v[134:137], v[186:187], off offset:64
	global_load_dwordx4 v[138:141], v[186:187], off offset:128
	global_load_dwordx4 v[142:145], v[186:187], off offset:192
	s_mov_b32 s0, s3
	s_waitcnt vmcnt(12)
	v_pk_fma_f32 v[214:215], v[146:147], v[26:27], v[214:215]
	v_pk_fma_f32 v[216:217], v[148:149], v[28:29], v[216:217]
	v_pk_fma_f32 v[218:219], v[6:7], v[30:31], v[218:219]
	v_pk_fma_f32 v[220:221], v[8:9], v[32:33], v[220:221]
	v_pk_fma_f32 v[222:223], v[150:151], v[34:35], v[222:223]
	v_pk_fma_f32 v[224:225], v[152:153], v[36:37], v[224:225]
	v_pk_fma_f32 v[226:227], v[154:155], v[180:181], v[226:227]
	v_pk_fma_f32 v[228:229], v[156:157], v[182:183], v[228:229]
	global_store_dwordx4 v[50:51], v[214:217], off
	global_store_dwordx4 v[50:51], v[218:221], off offset:64
	global_store_dwordx4 v[50:51], v[222:225], off offset:128
	global_store_dwordx4 v[50:51], v[226:229], off offset:192
	s_waitcnt vmcnt(12)
	v_pk_fma_f32 v[230:231], v[158:159], v[26:27], v[230:231]
	v_pk_fma_f32 v[232:233], v[160:161], v[28:29], v[232:233]
	v_pk_fma_f32 v[234:235], v[162:163], v[30:31], v[234:235]
	v_pk_fma_f32 v[236:237], v[164:165], v[32:33], v[236:237]
	v_pk_fma_f32 v[238:239], v[166:167], v[34:35], v[238:239]
	v_pk_fma_f32 v[240:241], v[168:169], v[36:37], v[240:241]
	v_pk_fma_f32 v[242:243], v[176:177], v[180:181], v[242:243]
	v_pk_fma_f32 v[244:245], v[178:179], v[182:183], v[244:245]
	global_store_dwordx4 v[56:57], v[230:233], off
	global_store_dwordx4 v[56:57], v[234:237], off offset:64
	global_store_dwordx4 v[56:57], v[238:241], off offset:128
	global_store_dwordx4 v[56:57], v[242:245], off offset:192
	s_waitcnt vmcnt(12)
	v_pk_fma_f32 v[96:97], v[46:47], v[26:27], v[96:97]
	v_pk_fma_f32 v[98:99], v[48:49], v[28:29], v[98:99]
	v_pk_fma_f32 v[100:101], v[42:43], v[30:31], v[100:101]
	v_pk_fma_f32 v[102:103], v[44:45], v[32:33], v[102:103]
	v_pk_fma_f32 v[104:105], v[38:39], v[34:35], v[104:105]
	v_pk_fma_f32 v[106:107], v[40:41], v[36:37], v[106:107]
	v_pk_fma_f32 v[108:109], v[22:23], v[180:181], v[108:109]
	v_pk_fma_f32 v[110:111], v[24:25], v[182:183], v[110:111]
	global_store_dwordx4 v[184:185], v[96:99], off
	global_store_dwordx4 v[184:185], v[100:103], off offset:64
	global_store_dwordx4 v[184:185], v[104:107], off offset:128
	global_store_dwordx4 v[184:185], v[108:111], off offset:192
	s_waitcnt vmcnt(12)
	v_pk_fma_f32 v[130:131], v[18:19], v[26:27], v[130:131]
	v_pk_fma_f32 v[132:133], v[20:21], v[28:29], v[132:133]
	v_pk_fma_f32 v[134:135], v[14:15], v[30:31], v[134:135]
	v_pk_fma_f32 v[136:137], v[16:17], v[32:33], v[136:137]
	v_pk_fma_f32 v[138:139], v[10:11], v[34:35], v[138:139]
	v_pk_fma_f32 v[140:141], v[12:13], v[36:37], v[140:141]
	v_pk_fma_f32 v[142:143], v[2:3], v[180:181], v[142:143]
	v_pk_fma_f32 v[144:145], v[4:5], v[182:183], v[144:145]
	global_store_dwordx4 v[186:187], v[130:133], off
	global_store_dwordx4 v[186:187], v[134:137], off offset:64
	global_store_dwordx4 v[186:187], v[138:141], off offset:128
	global_store_dwordx4 v[186:187], v[142:145], off offset:192
	s_and_b64 vcc, exec, s[34:35]
	s_cbranch_vccnz .LBB0_895

.LBB0_891:
	s_and_b32 s1, s0, 7
	s_mul_i32 s1, s1, s2
	s_ashr_i32 s0, s0, 3
	s_add_i32 s0, s1, s0
	s_ashr_i32 s1, s0, 31
	s_lshr_b32 s1, s1, 26
	s_add_i32 s1, s0, s1
	s_and_b32 s19, s1, 0xffffffc0
	s_sub_i32 s0, s0, s19
	s_lshl_b32 s1, s1, 4
	s_and_b32 s19, s1, 0xfffffc00
	s_lshl_b32 s1, s0, 7
	s_and_b32 s26, s1, 0x380
	s_lshl_b32 s0, s0, 4
	s_and_b32 s42, s0, 0xffffff80
	s_or_b32 s40, s19, s26
	s_ashr_i32 s43, s42, 31
	s_waitcnt vmcnt(16)
	s_ashr_i32 s41, s40, 31
	s_lshl_b64 s[0:1], s[42:43], 11
	s_lshl_b64 s[26:27], s[40:41], 11
	v_mov_b32_e32 v2, 0
	v_lshl_add_u64 v[96:97], v[70:71], 0, s[26:27]
	v_lshl_add_u64 v[98:99], v[72:73], 0, s[26:27]
	v_lshl_add_u64 v[100:101], v[74:75], 0, s[26:27]
	v_lshl_add_u64 v[102:103], v[76:77], 0, s[26:27]
	v_lshl_add_u64 v[104:105], v[78:79], 0, s[0:1]
	v_lshl_add_u64 v[106:107], v[80:81], 0, s[0:1]
	v_lshl_add_u64 v[108:109], v[82:83], 0, s[0:1]
	v_lshl_add_u64 v[110:111], v[84:85], 0, s[0:1]
	s_mov_b32 s19, 0
	v_mov_b32_e32 v3, v2
	v_mov_b32_e32 v4, v2
	v_mov_b32_e32 v5, v2
	v_mov_b32_e32 v6, v2
	v_mov_b32_e32 v7, v2
	v_mov_b32_e32 v8, v2
	v_mov_b32_e32 v9, v2
	v_mov_b32_e32 v10, v2
	v_mov_b32_e32 v11, v2
	v_mov_b32_e32 v12, v2
	v_mov_b32_e32 v13, v2
	v_mov_b32_e32 v14, v2
	v_mov_b32_e32 v15, v2
	v_mov_b32_e32 v16, v2
	v_mov_b32_e32 v17, v2
	v_mov_b32_e32 v18, v2
	v_mov_b32_e32 v19, v2
	v_mov_b32_e32 v20, v2
	v_mov_b32_e32 v21, v2
	v_mov_b32_e32 v22, v2
	v_mov_b32_e32 v23, v2
	v_mov_b32_e32 v24, v2
	v_mov_b32_e32 v25, v2
	v_mov_b32_e32 v26, v2
	v_mov_b32_e32 v27, v2
	v_mov_b32_e32 v28, v2
	v_mov_b32_e32 v29, v2
	v_mov_b32_e32 v30, v2
	v_mov_b32_e32 v31, v2
	v_mov_b32_e32 v32, v2
	v_mov_b32_e32 v33, v2
	v_mov_b32_e32 v34, v2
	v_mov_b32_e32 v35, v2
	v_mov_b32_e32 v36, v2
	v_mov_b32_e32 v37, v2
	v_mov_b32_e32 v38, v2
	v_mov_b32_e32 v39, v2
	v_mov_b32_e32 v40, v2
	v_mov_b32_e32 v41, v2
	v_mov_b32_e32 v42, v2
	v_mov_b32_e32 v43, v2
	v_mov_b32_e32 v44, v2
	v_mov_b32_e32 v45, v2
	v_mov_b32_e32 v46, v2
	v_mov_b32_e32 v47, v2
	v_mov_b32_e32 v48, v2
	v_mov_b32_e32 v49, v2
	v_mov_b32_e32 v50, v2
	v_mov_b32_e32 v51, v2
	v_mov_b32_e32 v52, v2
	v_mov_b32_e32 v53, v2
	v_mov_b32_e32 v54, v2
	v_mov_b32_e32 v55, v2
	v_mov_b32_e32 v56, v2
	v_mov_b32_e32 v57, v2
	v_mov_b32_e32 v58, v2
	v_mov_b32_e32 v59, v2
	v_mov_b32_e32 v60, v2
	v_mov_b32_e32 v61, v2
	v_mov_b32_e32 v62, v2
	v_mov_b32_e32 v63, v2
	v_mov_b32_e32 v64, v2
	v_mov_b32_e32 v65, v2
	v_and_b32_e32 v214, 63, v188
	v_lshrrev_b32_e32 v215, 3, v214
	v_and_b32_e32 v216, 7, v214
	v_xor_b32_e32 v216, v216, v215
	v_mul_u32_u24_e32 v246, 0x800, v215
	v_lshl_add_u32 v246, v216, 4, v246
	v_add_u32_e32 v247, 0x4000, v246
	v_add_u32_e32 v248, 0x8000, v246
	v_add_u32_e32 v249, 0xc000, v246
	v_lshrrev_b32_e32 v250, 6, v188
	v_lshlrev_b32_e32 v250, 12, v250
	v_readfirstlane_b32 s98, v96
	v_readfirstlane_b32 s99, v97
	v_readfirstlane_b32 s100, v104
	v_readfirstlane_b32 s101, v105
	s_add_u32 s98, s98, s46
	s_addc_u32 s99, s99, s47
	s_add_u32 s100, s100, s46
	s_addc_u32 s101, s101, s47
	s_waitcnt lgkmcnt(0)
	s_barrier

.LBB0_999:
	s_and_b32 s1, s0, 7
	s_mul_i32 s1, s1, s3
	s_ashr_i32 s0, s0, 3
	s_add_i32 s1, s1, s0
	s_mul_hi_i32 s0, s1, 0x2e8ba2e9
	s_lshr_b32 s26, s0, 31
	s_ashr_i32 s0, s0, 6
	s_add_i32 s0, s0, s26
	s_mul_i32 s26, s0, 0x160
	s_sub_i32 s1, s1, s26
	s_lshl_b32 s26, s0, 10
	s_lshl_b32 s0, s1, 7
	s_and_b32 s27, s0, 0x380
	s_lshl_b32 s0, s1, 4
	s_and_b32 s40, s0, 0xffffff80
	s_or_b32 s42, s26, s27
	s_ashr_i32 s41, s40, 31
	s_waitcnt vmcnt(8)
	s_ashr_i32 s43, s42, 31
	s_lshl_b64 s[0:1], s[40:41], 11
	s_lshl_b64 s[26:27], s[42:43], 11
	v_mov_b32_e32 v2, 0
	v_lshl_add_u64 v[94:95], v[70:71], 0, s[26:27]
	v_lshl_add_u64 v[96:97], v[72:73], 0, s[26:27]
	v_lshl_add_u64 v[98:99], v[74:75], 0, s[26:27]
	v_lshl_add_u64 v[100:101], v[76:77], 0, s[26:27]
	v_lshl_add_u64 v[102:103], v[78:79], 0, s[0:1]
	v_lshl_add_u64 v[104:105], v[80:81], 0, s[0:1]
	v_lshl_add_u64 v[106:107], v[82:83], 0, s[0:1]
	v_lshl_add_u64 v[108:109], v[84:85], 0, s[0:1]
	s_mov_b32 s33, 0
	v_mov_b32_e32 v3, v2
	v_mov_b32_e32 v4, v2
	v_mov_b32_e32 v5, v2
	v_mov_b32_e32 v6, v2
	v_mov_b32_e32 v7, v2
	v_mov_b32_e32 v8, v2
	v_mov_b32_e32 v9, v2
	v_mov_b32_e32 v10, v2
	v_mov_b32_e32 v11, v2
	v_mov_b32_e32 v12, v2
	v_mov_b32_e32 v13, v2
	v_mov_b32_e32 v14, v2
	v_mov_b32_e32 v15, v2
	v_mov_b32_e32 v16, v2
	v_mov_b32_e32 v17, v2
	v_mov_b32_e32 v18, v2
	v_mov_b32_e32 v19, v2
	v_mov_b32_e32 v20, v2
	v_mov_b32_e32 v21, v2
	v_mov_b32_e32 v22, v2
	v_mov_b32_e32 v23, v2
	v_mov_b32_e32 v24, v2
	v_mov_b32_e32 v25, v2
	v_mov_b32_e32 v26, v2
	v_mov_b32_e32 v27, v2
	v_mov_b32_e32 v28, v2
	v_mov_b32_e32 v29, v2
	v_mov_b32_e32 v30, v2
	v_mov_b32_e32 v31, v2
	v_mov_b32_e32 v32, v2
	v_mov_b32_e32 v33, v2
	v_mov_b32_e32 v34, v2
	v_mov_b32_e32 v35, v2
	v_mov_b32_e32 v36, v2
	v_mov_b32_e32 v37, v2
	v_mov_b32_e32 v38, v2
	v_mov_b32_e32 v39, v2
	v_mov_b32_e32 v40, v2
	v_mov_b32_e32 v41, v2
	v_mov_b32_e32 v42, v2
	v_mov_b32_e32 v43, v2
	v_mov_b32_e32 v44, v2
	v_mov_b32_e32 v45, v2
	v_mov_b32_e32 v46, v2
	v_mov_b32_e32 v47, v2
	v_mov_b32_e32 v48, v2
	v_mov_b32_e32 v49, v2
	v_mov_b32_e32 v50, v2
	v_mov_b32_e32 v51, v2
	v_mov_b32_e32 v52, v2
	v_mov_b32_e32 v53, v2
	v_mov_b32_e32 v54, v2
	v_mov_b32_e32 v55, v2
	v_mov_b32_e32 v56, v2
	v_mov_b32_e32 v57, v2
	v_mov_b32_e32 v58, v2
	v_mov_b32_e32 v59, v2
	v_mov_b32_e32 v60, v2
	v_mov_b32_e32 v61, v2
	v_mov_b32_e32 v62, v2
	v_mov_b32_e32 v63, v2
	v_mov_b32_e32 v64, v2
	v_mov_b32_e32 v65, v2
	v_and_b32_e32 v214, 63, v188
	v_lshrrev_b32_e32 v215, 3, v214
	v_and_b32_e32 v216, 7, v214
	v_xor_b32_e32 v216, v216, v215
	v_mul_u32_u24_e32 v246, 0x800, v215
	v_lshl_add_u32 v246, v216, 4, v246
	v_add_u32_e32 v247, 0x4000, v246
	v_add_u32_e32 v248, 0x8000, v246
	v_add_u32_e32 v249, 0xc000, v246
	v_lshrrev_b32_e32 v250, 6, v188
	v_lshlrev_b32_e32 v250, 12, v250
	v_readfirstlane_b32 s98, v94
	v_readfirstlane_b32 s99, v95
	v_readfirstlane_b32 s100, v102
	v_readfirstlane_b32 s101, v103
	s_add_u32 s98, s98, s46
	s_addc_u32 s99, s99, s47
	s_add_u32 s100, s100, s46
	s_addc_u32 s101, s101, s47
	s_waitcnt lgkmcnt(0)
	s_barrier

.LBB0_1052:
	s_or_b64 exec, exec, s[34:35]
	s_waitcnt lgkmcnt(0)
	v_mov_b32_e32 v2, v188
	s_andn2_b64 vcc, exec, s[38:39]
	s_barrier
	s_cbranch_vccnz .LBB0_1061
	s_mul_i32 s0, s58, 0x580000
	v_readlane_b32 s1, v254, 42
	s_add_u32 s34, s1, s0
	v_readlane_b32 s0, v254, 43
	s_addc_u32 s35, s0, 0
	s_lshr_b32 s2, s22, 7
	v_readlane_b32 s0, v254, 24
	s_mul_i32 s0, s2, s0
	v_readlane_b32 s1, v254, 25
	s_add_i32 s0, s0, s1
	s_ashr_i32 s1, s0, 31
	s_lshr_b32 s1, s1, 26
	s_add_i32 s1, s0, s1
	s_and_b32 s3, s1, 0xffffffc0
	s_sub_i32 s0, s0, s3
	s_lshl_b32 s1, s1, 4
	s_lshl_b32 s3, s0, 7
	s_and_b32 s1, s1, 0xfffffc00
	s_and_b32 s3, s3, 0x380
	s_or_b32 s1, s3, s1
	s_lshl_b32 s0, s0, 4
	s_and_b32 s3, s0, 0xffff80
	s_mul_hi_i32 s19, s1, 0x1600
	s_mulk_i32 s1, 0x1600
	v_bfe_u32 v13, v2, 3, 3
	v_and_b32_e32 v3, 63, v2
	v_ashrrev_i32_e32 v12, 6, v2
	s_add_u32 s0, s20, s1
	v_bitop3_b32 v0, v13, v2, 7 bitop3:0x78
	s_addc_u32 s1, s21, s19
	s_mul_i32 s26, s3, 0xb00
	v_lshlrev_b32_e32 v0, 4, v0
	v_lshl_add_u32 v112, v3, 4, 0
	v_lshl_or_b32 v15, v12, 5, v13
	s_movk_i32 s3, 0xb00
	s_ashr_i32 s27, s26, 31
	v_lshl_add_u64 v[4:5], s[0:1], 0, v[0:1]
	v_mad_i64_i32 v[8:9], s[0:1], v15, s3, 0
	v_lshl_add_u32 v113, v12, 12, v112
	s_lshl_b64 s[26:27], s[26:27], 1
	v_lshlrev_b32_e32 v14, 2, v12
	v_lshlrev_b64 v[70:71], 1, v[8:9]
	v_readfirstlane_b32 s0, v113
	s_add_u32 s26, s34, s26
	v_lshl_add_u64 v[8:9], v[4:5], 0, v[70:71]
	v_add_u32_e32 v114, 0x8000, v113
	s_mov_b32 m0, s0
	v_or_b32_e32 v3, 1, v14
	s_addc_u32 s27, s35, s27
	global_load_lds_dwordx4 v[8:9], off
	v_readfirstlane_b32 s0, v114
	v_lshl_or_b32 v8, v3, 3, v13
	v_lshl_add_u64 v[6:7], s[26:27], 0, v[0:1]
	s_mov_b32 m0, s0
	v_mad_i64_i32 v[8:9], s[0:1], v8, s3, 0
	v_lshl_add_u32 v115, v3, 10, v112
	v_lshl_add_u64 v[10:11], v[6:7], 0, v[70:71]
	v_lshlrev_b64 v[72:73], 1, v[8:9]
	v_readfirstlane_b32 s0, v115
	global_load_lds_dwordx4 v[10:11], off
	v_lshl_add_u64 v[8:9], v[4:5], 0, v[72:73]
	v_add_u32_e32 v116, 0x8000, v115
	s_mov_b32 m0, s0
	v_or_b32_e32 v16, 2, v14
	global_load_lds_dwordx4 v[8:9], off
	v_readfirstlane_b32 s0, v116
	v_lshl_or_b32 v8, v16, 3, v13
	s_mov_b32 m0, s0
	v_mad_i64_i32 v[8:9], s[0:1], v8, s3, 0
	v_lshl_add_u32 v117, v16, 10, v112
	v_lshl_add_u64 v[10:11], v[6:7], 0, v[72:73]
	v_lshlrev_b64 v[74:75], 1, v[8:9]
	v_add_u32_e32 v118, 0x8000, v117
	v_readfirstlane_b32 s0, v117
	global_load_lds_dwordx4 v[10:11], off
	v_lshl_add_u64 v[8:9], v[4:5], 0, v[74:75]
	s_mov_b32 m0, s0
	v_readfirstlane_b32 s0, v118
	v_lshl_add_u64 v[10:11], v[6:7], 0, v[74:75]
	global_load_lds_dwordx4 v[8:9], off
	s_mov_b32 m0, s0
	v_lshlrev_b32_e32 v122, 9, v3
	global_load_lds_dwordx4 v[10:11], off
	v_or_b32_e32 v10, 3, v14
	v_lshl_or_b32 v8, v10, 3, v13
	v_mad_i64_i32 v[8:9], s[0:1], v8, s3, 0
	v_lshl_add_u32 v119, v10, 10, v112
	v_lshlrev_b64 v[76:77], 1, v[8:9]
	v_add_u32_e32 v120, 0x8000, v119
	v_readfirstlane_b32 s0, v119
	v_lshl_add_u64 v[4:5], v[4:5], 0, v[76:77]
	s_mov_b32 m0, s0
	v_readfirstlane_b32 s0, v120
	v_lshl_add_u64 v[6:7], v[6:7], 0, v[76:77]
	global_load_lds_dwordx4 v[4:5], off
	s_mov_b32 m0, s0
	v_ashrrev_i32_e32 v8, 7, v2
	global_load_lds_dwordx4 v[6:7], off
	v_and_b32_e32 v7, 15, v2
	v_bfe_u32 v5, v2, 4, 2
	v_and_b32_e32 v4, 1, v12
	v_lshlrev_b32_e32 v3, 13, v8
	v_lshlrev_b32_e32 v6, 7, v7
	v_and_b32_e32 v9, 7, v2
	v_add3_u32 v125, 0, v3, v6
	v_lshlrev_b32_e32 v3, 13, v4
	v_bitop3_b32 v2, v5, v2, 7 bitop3:0x78
	v_add3_u32 v126, 0, v3, v6
	v_lshlrev_b32_e32 v6, 2, v5
	v_lshlrev_b32_e32 v128, 4, v2
	v_bitop3_b32 v2, v5, v9, 4 bitop3:0x36
	s_movk_i32 s3, 0x1600
	v_or_b32_e32 v5, 8, v15
	v_lshl_or_b32 v127, v8, 6, v7
	v_mad_i64_i32 v[8:9], s[0:1], v5, s3, 0
	v_or_b32_e32 v5, 16, v15
	v_lshlrev_b32_e32 v124, 9, v10
	v_mad_i64_i32 v[10:11], s[0:1], v5, s3, 0
	v_or_b32_e32 v5, 24, v15
	v_lshlrev_b32_e32 v121, 11, v12
	v_lshlrev_b32_e32 v129, 4, v2
	v_mad_i64_i32 v[2:3], s[0:1], v15, s3, 0
	v_mad_i64_i32 v[12:13], s[0:1], v5, s3, 0
	v_readlane_b32 s26, v254, 60
	v_readlane_b32 s0, v254, 62
	v_lshlrev_b32_e32 v4, 6, v4
	v_or_b32_e32 v2, v2, v0
	v_readlane_b32 s27, v254, 61
	v_or_b32_e32 v8, v8, v0
	v_or_b32_e32 v10, v10, v0
	v_or_b32_e32 v12, v12, v0
	v_readlane_b32 s1, v254, 63
	v_lshlrev_b32_e32 v123, 9, v16
	v_lshl_add_u64 v[78:79], s[20:21], 0, v[0:1]
	v_lshl_add_u64 v[80:81], s[34:35], 0, v[0:1]
	v_lshl_add_u64 v[82:83], s[26:27], 0, v[2:3]
	v_lshl_add_u64 v[84:85], s[26:27], 0, v[8:9]
	v_lshl_add_u64 v[86:87], s[26:27], 0, v[10:11]
	v_lshl_add_u64 v[88:89], s[26:27], 0, v[12:13]
	v_lshl_add_u64 v[90:91], s[0:1], 0, v[2:3]
	v_lshl_add_u64 v[92:93], s[0:1], 0, v[8:9]
	v_lshl_add_u64 v[94:95], s[0:1], 0, v[10:11]
	v_lshl_add_u64 v[96:97], s[0:1], 0, v[12:13]
	v_lshlrev_b32_e32 v0, 2, v4
	v_lshlrev_b32_e32 v98, 2, v6
	s_mov_b32 s0, s56
	s_waitcnt vmcnt(0)
	s_branch .LBB0_1055

.LBB0_1057:
	s_and_b32 s1, s0, 7
	s_mul_i32 s1, s1, s2
	s_ashr_i32 s0, s0, 3
	s_add_i32 s0, s1, s0
	s_ashr_i32 s1, s0, 31
	s_lshr_b32 s1, s1, 26
	s_add_i32 s1, s0, s1
	s_and_b32 s19, s1, 0xffffffc0
	s_sub_i32 s0, s0, s19
	s_lshl_b32 s1, s1, 4
	s_lshl_b32 s19, s0, 7
	s_and_b32 s1, s1, 0xfffffc00
	s_and_b32 s19, s19, 0x380
	s_lshl_b32 s0, s0, 4
	s_waitcnt vmcnt(16)
	s_and_b32 s38, s0, 0xffffff80
	s_or_b32 s19, s1, s19
	v_mov_b32_e32 v2, 0
	s_ashr_i32 s39, s38, 31
	v_mad_i64_i32 v[66:67], s[0:1], s19, v208, v[82:83]
	v_mad_i64_i32 v[68:69], s[0:1], s19, v208, v[84:85]
	v_mad_i64_i32 v[100:101], s[0:1], s19, v208, v[86:87]
	v_mad_i64_i32 v[102:103], s[0:1], s19, v208, v[88:89]
	v_mad_i64_i32 v[104:105], s[0:1], s38, v208, v[90:91]
	v_mad_i64_i32 v[106:107], s[0:1], s38, v208, v[92:93]
	v_mad_i64_i32 v[108:109], s[0:1], s38, v208, v[94:95]
	v_mad_i64_i32 v[110:111], s[0:1], s38, v208, v[96:97]
	s_mov_b32 s22, 0
	v_mov_b32_e32 v3, v2
	v_mov_b32_e32 v4, v2
	v_mov_b32_e32 v5, v2
	v_mov_b32_e32 v6, v2
	v_mov_b32_e32 v7, v2
	v_mov_b32_e32 v8, v2
	v_mov_b32_e32 v9, v2
	v_mov_b32_e32 v10, v2
	v_mov_b32_e32 v11, v2
	v_mov_b32_e32 v12, v2
	v_mov_b32_e32 v13, v2
	v_mov_b32_e32 v14, v2
	v_mov_b32_e32 v15, v2
	v_mov_b32_e32 v16, v2
	v_mov_b32_e32 v17, v2
	v_mov_b32_e32 v18, v2
	v_mov_b32_e32 v19, v2
	v_mov_b32_e32 v20, v2
	v_mov_b32_e32 v21, v2
	v_mov_b32_e32 v22, v2
	v_mov_b32_e32 v23, v2
	v_mov_b32_e32 v24, v2
	v_mov_b32_e32 v25, v2
	v_mov_b32_e32 v26, v2
	v_mov_b32_e32 v27, v2
	v_mov_b32_e32 v28, v2
	v_mov_b32_e32 v29, v2
	v_mov_b32_e32 v30, v2
	v_mov_b32_e32 v31, v2
	v_mov_b32_e32 v32, v2
	v_mov_b32_e32 v33, v2
	v_mov_b32_e32 v34, v2
	v_mov_b32_e32 v35, v2
	v_mov_b32_e32 v36, v2
	v_mov_b32_e32 v37, v2
	v_mov_b32_e32 v38, v2
	v_mov_b32_e32 v39, v2
	v_mov_b32_e32 v40, v2
	v_mov_b32_e32 v41, v2
	v_mov_b32_e32 v42, v2
	v_mov_b32_e32 v43, v2
	v_mov_b32_e32 v44, v2
	v_mov_b32_e32 v45, v2
	v_mov_b32_e32 v46, v2
	v_mov_b32_e32 v47, v2
	v_mov_b32_e32 v48, v2
	v_mov_b32_e32 v49, v2
	v_mov_b32_e32 v50, v2
	v_mov_b32_e32 v51, v2
	v_mov_b32_e32 v52, v2
	v_mov_b32_e32 v53, v2
	v_mov_b32_e32 v54, v2
	v_mov_b32_e32 v55, v2
	v_mov_b32_e32 v56, v2
	v_mov_b32_e32 v57, v2
	v_mov_b32_e32 v58, v2
	v_mov_b32_e32 v59, v2
	v_mov_b32_e32 v60, v2
	v_mov_b32_e32 v61, v2
	v_mov_b32_e32 v62, v2
	v_mov_b32_e32 v63, v2
	v_mov_b32_e32 v64, v2
	v_mov_b32_e32 v65, v2
	s_mov_b32 s24, s25
	v_and_b32_e32 v214, 63, v188
	v_lshrrev_b32_e32 v215, 3, v214
	v_and_b32_e32 v216, 7, v214
	v_xor_b32_e32 v216, v216, v215
	v_mul_u32_u24_e32 v246, 0x1600, v215
	v_lshl_add_u32 v246, v216, 4, v246
	v_add_u32_e32 v247, 0xb000, v246
	v_add_u32_e32 v248, 0x16000, v246
	v_add_u32_e32 v249, 0x21000, v246
	v_lshrrev_b32_e32 v250, 6, v188
	v_lshlrev_b32_e32 v250, 12, v250
	v_readfirstlane_b32 s98, v66
	v_readfirstlane_b32 s99, v67
	v_readfirstlane_b32 s100, v104
	v_readfirstlane_b32 s101, v105
	s_add_u32 s98, s98, s42
	s_addc_u32 s99, s99, s43
	s_add_u32 s100, s100, s42
	s_addc_u32 s101, s101, s43
	s_waitcnt vmcnt(16) lgkmcnt(0)
	s_barrier
